# differential mixer: waves 4-7 run a staggered copy of the tile loop (barrier after the QK block), waves 0-3 keep the previous body
# speedup vs baseline: 1.0101x; 1.0043x over previous
.LBB0_734:
	s_lshl_b32 s1, s11, 5
	s_and_b32 s0, s11, 0xffffff00
	s_and_b32 s1, s1, 0xe0
	s_or_b32 s0, s1, s0
	s_bfe_u32 s1, s11, 0x50003
	s_or_b32 s6, s0, s1
	v_readlane_b32 s0, v254, 15
	v_readlane_b32 s1, v254, 16
	s_and_b64 s[0:1], s[0:1], exec
	v_mov_b32_e32 v0, v185
	s_cselect_b32 s14, s6, s11
	s_lshl_b32 s6, s14, 3
	v_mbcnt_lo_u32_b32 v0, -1, v0
	v_mbcnt_hi_u32_b32 v12, -1, v0
	v_readlane_b32 s0, v252, 16
	s_and_b32 s12, s6, 0xc0
	s_ashr_i32 s15, s14, 5
	v_add_u32_e32 v2, s0, v12
	s_mov_b64 s[0:1], s[40:41]
	s_lshl_b32 s6, s12, 1
	s_add_u32 s6, s0, s6
	s_addc_u32 s7, s1, 0
	s_add_u32 s16, s6, 0xba00a00
	s_addc_u32 s17, s7, 0
	s_add_u32 s8, s6, 0xba00c00
	s_addc_u32 s9, s7, 0
	s_add_u32 s6, s6, 0xba00e00
	s_addc_u32 s7, s7, 0
	s_lshl_b32 s14, s14, 8
	v_and_b32_e32 v13, 31, v12
	s_lshl_b32 s13, s15, 11
	s_and_b32 s18, s14, 0x700
	s_lshl_b32 s14, s15, 8
	v_readlane_b32 s15, v255, 6
	v_bfe_u32 v14, v12, 5, 1
	v_lshlrev_b32_e32 v184, 4, v14
	v_or_b32_e32 v0, s15, v13
	s_or_b32 s15, s18, s13
	v_add_u32_e32 v192, s15, v0
	v_mov_b64_e32 v[0:1], s[16:17]
	v_mad_i64_i32 v[0:1], s[16:17], v192, s33, v[0:1]
	v_lshl_add_u64 v[0:1], v[0:1], 0, v[184:185]
	global_load_dwordx4 v[128:131], v[0:1], off
	global_load_dwordx4 v[132:135], v[0:1], off offset:32
	global_load_dwordx4 v[136:139], v[0:1], off offset:64
	global_load_dwordx4 v[140:143], v[0:1], off offset:96
	v_ashrrev_i32_e32 v0, 31, v2
	v_lshrrev_b32_e32 v0, 29, v0
	v_add_u32_e32 v0, v2, v0
	v_ashrrev_i32_e32 v239, 3, v0
	v_and_b32_e32 v0, -8, v0
	v_sub_u32_e32 v15, v2, v0
	v_ashrrev_i32_e32 v240, 3, v2
	v_add_u32_e32 v2, s13, v239
	v_mov_b64_e32 v[0:1], s[8:9]
	v_mad_i64_i32 v[0:1], s[16:17], v2, s33, v[0:1]
	v_lshlrev_b32_e32 v2, 3, v15
	v_ashrrev_i32_e32 v3, 31, v2
	v_lshlrev_b64 v[8:9], 1, v[2:3]
	v_lshl_add_u64 v[0:1], v[0:1], 0, v[8:9]
	global_load_dwordx4 v[0:3], v[0:1], off
	v_and_b32_e32 v6, 7, v12
	v_add_u32_e32 v7, s13, v240
	v_mov_b64_e32 v[4:5], s[6:7]
	v_mad_i64_i32 v[4:5], s[16:17], v7, s33, v[4:5]
	v_lshlrev_b32_e32 v10, 4, v6
	v_mov_b32_e32 v11, v185
	v_lshl_add_u64 v[4:5], v[4:5], 0, v[10:11]
	global_load_dwordx4 v[4:7], v[4:5], off
	v_mul_lo_u32 v16, v239, s81
	v_lshlrev_b32_e32 v15, 4, v15
	v_add3_u32 v241, 0, v16, v15
	v_lshlrev_b32_e32 v191, 2, v14
	v_lshl_add_u64 v[196:197], s[6:7], 0, v[10:11]
	s_or_b32 s7, s13, 64
	v_lshl_add_u64 v[194:195], s[8:9], 0, v[8:9]
	s_add_i32 s14, s14, 0x8000
	v_ashrrev_i32_e32 v193, 31, v192
	v_lshlrev_b32_e32 v190, 3, v14
	s_mov_b32 s6, 2
	s_waitcnt vmcnt(1)
	ds_write_b128 v241, v[0:3]
	v_mul_lo_u32 v0, v240, s80
	v_add3_u32 v242, 0, v0, v10
	v_lshrrev_b32_e32 v0, 2, v12
	v_lshlrev_b32_e32 v1, 2, v12
	v_and_b32_e32 v3, 16, v12
	v_and_or_b32 v0, v0, 3, v191
	v_and_or_b32 v1, v1, 12, v3
	v_mul_u32_u24_e32 v0, 0xc0, v0
	v_lshlrev_b32_e32 v1, 1, v1
	s_waitcnt vmcnt(0)
	ds_write_b128 v242, v[4:7] offset:26624
	v_add3_u32 v243, 0, v0, v1
	v_add_u32_e32 v0, s7, v239
	s_waitcnt lgkmcnt(0)
	s_barrier
	v_mad_i64_i32 v[0:1], s[8:9], v0, s33, v[194:195]
	global_load_dwordx4 v[82:85], v[0:1], off
	v_add_u32_e32 v0, s7, v240
	v_mad_i64_i32 v[0:1], s[8:9], v0, s33, v[196:197]
	global_load_dwordx4 v[86:89], v[0:1], off
	v_mul_u32_u24_e32 v2, 0xd0, v13
	v_add3_u32 v184, 0, v2, v184
	ds_read_b128 v[16:19], v184 offset:6656
	ds_read_b128 v[0:3], v184
	ds_read_b128 v[32:35], v184 offset:32
	ds_read_b128 v[36:39], v184 offset:6688
	ds_read_b64_tr_b16 v[66:67], v243 offset:26624
	ds_read_b64_tr_b16 v[68:69], v243 offset:28160
	ds_read_b64_tr_b16 v[98:99], v243 offset:29696
	ds_read_b64_tr_b16 v[100:101], v243 offset:31232
	ds_read_b64_tr_b16 v[94:95], v243 offset:32768
	ds_read_b64_tr_b16 v[96:97], v243 offset:34304
	ds_read_b64_tr_b16 v[90:91], v243 offset:35840
	ds_read_b64_tr_b16 v[92:93], v243 offset:37376
	ds_read_b64_tr_b16 v[102:103], v243 offset:26688
	ds_read_b64_tr_b16 v[104:105], v243 offset:28224
	ds_read_b64_tr_b16 v[114:115], v243 offset:29760
	ds_read_b64_tr_b16 v[116:117], v243 offset:31296
	ds_read_b64_tr_b16 v[110:111], v243 offset:32832
	ds_read_b64_tr_b16 v[112:113], v243 offset:34368
	ds_read_b64_tr_b16 v[106:107], v243 offset:35904
	ds_read_b64_tr_b16 v[108:109], v243 offset:37440
	s_waitcnt lgkmcnt(14)
	v_mfma_f32_32x32x16_bf16 v[0:15], v[0:3], v[128:131], 0
	v_mfma_f32_32x32x16_bf16 v[16:31], v[16:19], v[128:131], 0
	v_mfma_f32_32x32x16_bf16 v[0:15], v[32:35], v[132:135], v[0:15]
	v_mfma_f32_32x32x16_bf16 v[16:31], v[36:39], v[132:135], v[16:31]
	s_nop 15
	s_nop 7
	s_nop 0
	v_max3_f32 v32, v0, v1, v16
	v_max3_f32 v33, v2, v3, v17
	s_nop 0
	v_max3_f32 v32, v32, v18, v19
	v_max3_f32 v33, v33, v6, v7
	s_nop 0
	v_max3_f32 v32, v32, v4, v5
	v_max3_f32 v33, v33, v22, v23
	s_nop 0
	v_max3_f32 v32, v32, v20, v21
	v_max3_f32 v33, v33, v10, v11
	s_nop 0
	v_max3_f32 v32, v32, v8, v9
	v_max3_f32 v33, v33, v26, v27
	s_nop 0
	v_max3_f32 v32, v32, v24, v25
	v_max3_f32 v33, v33, v14, v15
	s_nop 0
	v_max3_f32 v32, v32, v12, v13
	v_max3_f32 v33, v33, v30, v31
	s_nop 0
	v_max3_f32 v32, v32, v28, v29
	s_nop 0
	v_max_f32_e32 v32, v32, v33
	s_nop 0
	v_mov_b32_e32 v33, v32
	s_nop 1
	v_permlane32_swap_b32_e32 v32, v33
	v_max_f32_e32 v33, v33, v33
	v_max_f32_e32 v32, v32, v32
	v_max_f32_e32 v32, v32, v33
	v_sub_f32_e32 v0, v0, v32
	v_sub_f32_e32 v1, v1, v32
	v_sub_f32_e32 v16, v16, v32
	v_sub_f32_e32 v17, v17, v32
	v_exp_f32_e32 v0, v0
	v_exp_f32_e32 v1, v1
	v_sub_f32_e32 v2, v2, v32
	v_sub_f32_e32 v3, v3, v32
	v_sub_f32_e32 v33, v4, v32
	v_sub_f32_e32 v34, v5, v32
	v_exp_f32_e32 v4, v16
	v_exp_f32_e32 v5, v17
	v_sub_f32_e32 v18, v18, v32
	v_sub_f32_e32 v19, v19, v32
	v_exp_f32_e32 v2, v2
	v_exp_f32_e32 v3, v3
	v_sub_f32_e32 v35, v6, v32
	v_sub_f32_e32 v36, v7, v32
	v_exp_f32_e32 v6, v18
	v_exp_f32_e32 v7, v19
	v_sub_f32_e32 v20, v20, v32
	v_sub_f32_e32 v21, v21, v32
	v_sub_f32_e32 v37, v8, v32
	v_sub_f32_e32 v38, v9, v32
	v_sub_f32_e32 v41, v12, v32
	v_exp_f32_e32 v8, v33
	v_exp_f32_e32 v9, v34
	v_exp_f32_e32 v12, v35
	v_pk_add_f32 v[34:35], v[0:1], 0 op_sel_hi:[1,0]
	v_sub_f32_e32 v39, v10, v32
	v_sub_f32_e32 v40, v11, v32
	v_exp_f32_e32 v10, v20
	v_exp_f32_e32 v11, v21
	v_pk_add_f32 v[34:35], v[4:5], v[34:35]
	v_sub_f32_e32 v22, v22, v32
	v_sub_f32_e32 v23, v23, v32
	v_sub_f32_e32 v42, v13, v32
	v_exp_f32_e32 v13, v36
	v_pk_add_f32 v[34:35], v[2:3], v[34:35]
	v_sub_f32_e32 v43, v14, v32
	v_sub_f32_e32 v44, v15, v32
	v_exp_f32_e32 v14, v22
	v_exp_f32_e32 v15, v23
	v_pk_add_f32 v[34:35], v[6:7], v[34:35]
	v_sub_f32_e32 v24, v24, v32
	v_sub_f32_e32 v25, v25, v32
	v_exp_f32_e32 v16, v37
	v_exp_f32_e32 v17, v38
	v_pk_add_f32 v[34:35], v[8:9], v[34:35]
	v_exp_f32_e32 v18, v24
	v_exp_f32_e32 v19, v25
	v_pk_add_f32 v[34:35], v[10:11], v[34:35]
	v_sub_f32_e32 v26, v26, v32
	v_sub_f32_e32 v27, v27, v32
	v_exp_f32_e32 v20, v39
	v_exp_f32_e32 v21, v40
	v_pk_add_f32 v[34:35], v[12:13], v[34:35]
	v_exp_f32_e32 v22, v26
	v_exp_f32_e32 v23, v27
	v_pk_add_f32 v[34:35], v[14:15], v[34:35]
	v_sub_f32_e32 v28, v28, v32
	v_sub_f32_e32 v29, v29, v32
	v_exp_f32_e32 v24, v41
	v_exp_f32_e32 v25, v42
	v_pk_add_f32 v[34:35], v[16:17], v[34:35]
	v_exp_f32_e32 v26, v28
	v_exp_f32_e32 v27, v29
	v_pk_add_f32 v[34:35], v[18:19], v[34:35]
	v_sub_f32_e32 v30, v30, v32
	v_sub_f32_e32 v31, v31, v32
	v_exp_f32_e32 v28, v43
	v_exp_f32_e32 v29, v44
	v_pk_add_f32 v[34:35], v[20:21], v[34:35]
	v_exp_f32_e32 v30, v30
	v_exp_f32_e32 v31, v31
	v_pk_add_f32 v[34:35], v[22:23], v[34:35]
	v_cvt_pk_bf16_f32 v0, v0, v1
	v_pk_add_f32 v[34:35], v[24:25], v[34:35]
	v_cvt_pk_bf16_f32 v1, v2, v3
	v_pk_add_f32 v[34:35], v[26:27], v[34:35]
	v_cvt_pk_bf16_f32 v2, v8, v9
	v_pk_add_f32 v[34:35], v[28:29], v[34:35]
	v_cvt_pk_bf16_f32 v3, v12, v13
	v_pk_add_f32 v[34:35], v[30:31], v[34:35]
	v_cvt_pk_bf16_f32 v36, v4, v5
	v_pk_add_f32 v[34:35], v[34:35], v[34:35] op_sel_hi:[0,1]
	v_mov_b32_e32 v33, v35
	v_pk_add_f32 v[198:199], v[32:33], 0 op_sel_hi:[1,0]
	v_cvt_pk_bf16_f32 v32, v16, v17
	v_cvt_pk_bf16_f32 v33, v20, v21
	v_cvt_pk_bf16_f32 v34, v24, v25
	v_cvt_pk_bf16_f32 v35, v28, v29
	v_cvt_pk_bf16_f32 v37, v6, v7
	v_cvt_pk_bf16_f32 v38, v10, v11
	v_cvt_pk_bf16_f32 v39, v14, v15
	v_cvt_pk_bf16_f32 v40, v18, v19
	v_cvt_pk_bf16_f32 v41, v22, v23
	v_cvt_pk_bf16_f32 v42, v26, v27
	v_cvt_pk_bf16_f32 v43, v30, v31
	v_mfma_f32_32x32x16_bf16 v[16:31], v[66:69], v[0:3], 0
	v_add_f32_e64 v48, -v198, neg(0)
	v_add_f32_e64 v49, -v199, neg(0)
	s_waitcnt lgkmcnt(6)
	v_mfma_f32_32x32x16_bf16 v[0:15], v[102:105], v[0:3], 0
	v_mfma_f32_32x32x16_bf16 v[16:31], v[98:101], v[32:35], v[16:31]
	s_waitcnt lgkmcnt(4)
	v_mfma_f32_32x32x16_bf16 v[0:15], v[114:117], v[32:35], v[0:15]
	ds_read_b128 v[50:53], v184 offset:6720
	ds_read_b128 v[70:73], v184 offset:6752
	ds_read_b128 v[32:35], v184 offset:64
	ds_read_b128 v[74:77], v184 offset:96
	v_mfma_f32_32x32x16_bf16 v[16:31], v[94:97], v[36:39], v[16:31]
	s_waitcnt lgkmcnt(6)
	v_mfma_f32_32x32x16_bf16 v[0:15], v[110:113], v[36:39], v[0:15]
	v_mfma_f32_32x32x16_bf16 v[16:31], v[90:93], v[40:43], v[16:31]
	s_waitcnt lgkmcnt(4)
	v_mfma_f32_32x32x16_bf16 v[0:15], v[106:109], v[40:43], v[0:15]
	s_waitcnt lgkmcnt(1)
	v_mfma_f32_32x32x16_bf16 v[32:47], v[32:35], v[136:139], 0
	s_movk_i32 s7, 0x80
	v_mfma_f32_32x32x16_bf16 v[50:65], v[50:53], v[136:139], 0
	s_waitcnt lgkmcnt(0)
	v_mfma_f32_32x32x16_bf16 v[32:47], v[74:77], v[140:143], v[32:47]
	v_mfma_f32_32x32x16_bf16 v[50:65], v[70:73], v[140:143], v[50:65]
	s_nop 15
	s_nop 7
	s_waitcnt vmcnt(1)
	ds_write_b128 v241, v[82:85] offset:13312
	s_waitcnt vmcnt(0)
	ds_write_b128 v242, v[86:89] offset:38912
	v_max3_f32 v49, v32, v33, v50
	v_max3_f32 v70, v34, v35, v51
	s_waitcnt lgkmcnt(0)
	s_barrier
	v_max3_f32 v49, v49, v52, v53
	v_max3_f32 v70, v70, v38, v39
	s_nop 0
	v_max3_f32 v49, v49, v36, v37
	v_max3_f32 v70, v70, v56, v57
	s_nop 0
	v_max3_f32 v49, v49, v54, v55
	v_max3_f32 v70, v70, v42, v43
	s_nop 0
	v_max3_f32 v49, v49, v40, v41
	v_max3_f32 v70, v70, v60, v61
	s_nop 0
	v_max3_f32 v49, v49, v58, v59
	v_max3_f32 v70, v70, v46, v47
	s_nop 0
	v_max3_f32 v49, v49, v44, v45
	v_max3_f32 v70, v70, v64, v65
	s_nop 0
	v_max3_f32 v49, v49, v62, v63
	s_nop 0
	v_max_f32_e32 v49, v49, v70
	s_nop 0
	v_mov_b32_e32 v70, v49
	s_nop 1
	v_permlane32_swap_b32_e32 v49, v70
	v_max_f32_e32 v70, v70, v70
	v_max_f32_e32 v49, v49, v49
	v_max_f32_e32 v80, v49, v70
	v_sub_f32_e32 v32, v32, v80
	v_sub_f32_e32 v33, v33, v80
	v_sub_f32_e32 v34, v34, v80
	v_sub_f32_e32 v35, v35, v80
	v_sub_f32_e32 v36, v36, v80
	v_sub_f32_e32 v37, v37, v80
	v_sub_f32_e32 v38, v38, v80
	v_sub_f32_e32 v39, v39, v80
	v_sub_f32_e32 v49, v50, v80
	v_sub_f32_e32 v50, v51, v80
	v_sub_f32_e32 v51, v52, v80
	v_sub_f32_e32 v52, v53, v80
	v_sub_f32_e32 v53, v54, v80
	v_sub_f32_e32 v70, v55, v80
	v_sub_f32_e32 v125, v58, v80
	v_sub_f32_e32 v127, v59, v80
	v_sub_f32_e32 v150, v62, v80
	v_sub_f32_e32 v151, v63, v80
	v_exp_f32_e32 v54, v32
	v_exp_f32_e32 v55, v33
	v_exp_f32_e32 v58, v34
	v_exp_f32_e32 v59, v35
	v_exp_f32_e32 v62, v36
	v_exp_f32_e32 v63, v37
	v_exp_f32_e32 v120, v38
	v_exp_f32_e32 v121, v39
	v_sub_f32_e32 v71, v56, v80
	v_sub_f32_e32 v40, v40, v80
	v_sub_f32_e32 v41, v41, v80
	v_sub_f32_e32 v42, v42, v80
	v_sub_f32_e32 v43, v43, v80
	v_sub_f32_e32 v44, v44, v80
	v_cvt_pk_bf16_f32 v32, v54, v55
	v_cvt_pk_bf16_f32 v33, v58, v59
	v_cvt_pk_bf16_f32 v34, v62, v63
	v_cvt_pk_bf16_f32 v35, v120, v121
	v_sub_f32_e32 v147, v45, v80
	v_sub_f32_e32 v152, v46, v80
	v_sub_f32_e32 v153, v64, v80
	v_sub_f32_e32 v154, v47, v80
	v_sub_f32_e32 v155, v65, v80
	v_exp_f32_e32 v119, v70
	v_exp_f32_e32 v122, v71
	v_mfma_f32_32x32x16_bf16 v[64:79], v[66:69], v[32:35], 0
	v_exp_f32_e32 v124, v40
	v_exp_f32_e32 v126, v125
	v_exp_f32_e32 v125, v41
	v_exp_f32_e32 v144, v42
	v_exp_f32_e32 v145, v43
	v_exp_f32_e32 v146, v44
	v_exp_f32_e32 v147, v147
	v_mfma_f32_32x32x16_bf16 v[32:47], v[102:105], v[32:35], 0
	v_exp_f32_e32 v102, v152
	v_exp_f32_e32 v103, v154
	v_sub_f32_e32 v81, v57, v80
	v_sub_f32_e32 v148, v60, v80
	v_sub_f32_e32 v149, v61, v80
	v_exp_f32_e32 v57, v50
	v_exp_f32_e32 v60, v51
	v_exp_f32_e32 v61, v52
	v_exp_f32_e32 v118, v53
	v_cvt_pk_bf16_f32 v50, v124, v125
	v_cvt_pk_bf16_f32 v51, v144, v145
	v_cvt_pk_bf16_f32 v52, v146, v147
	v_cvt_pk_bf16_f32 v53, v102, v103
	v_exp_f32_e32 v56, v49
	v_exp_f32_e32 v123, v81
	v_mfma_f32_32x32x16_bf16 v[64:79], v[98:101], v[50:53], v[64:79]
	v_exp_f32_e32 v127, v127
	v_exp_f32_e32 v98, v148
	v_exp_f32_e32 v99, v149
	v_exp_f32_e32 v100, v150
	v_exp_f32_e32 v101, v151
	v_exp_f32_e32 v104, v153
	v_exp_f32_e32 v105, v155
	v_mfma_f32_32x32x16_bf16 v[32:47], v[114:117], v[50:53], v[32:47]
	v_add_f32_e64 v50, v54, 0
	v_add_f32_e64 v51, v55, 0
	v_cvt_pk_bf16_f32 v52, v118, v119
	v_add_f32_e64 v50, v56, v50
	v_add_f32_e64 v51, v57, v51
	v_cvt_pk_bf16_f32 v53, v122, v123
	v_pk_add_f32 v[54:55], v[58:59], v[50:51]
	v_cvt_pk_bf16_f32 v50, v56, v57
	v_pk_add_f32 v[54:55], v[60:61], v[54:55]
	v_cvt_pk_bf16_f32 v51, v60, v61
	v_pk_add_f32 v[54:55], v[62:63], v[54:55]
	v_mov_b32_e32 v49, v48
	v_mfma_f32_32x32x16_bf16 v[64:79], v[94:97], v[50:53], v[64:79]
	v_add_f32_e64 v54, v118, v54
	v_add_f32_e64 v55, v119, v55
	v_mov_b32_e32 v56, v48
	v_add_f32_e64 v54, v120, v54
	v_add_f32_e64 v55, v121, v55
	v_mov_b32_e32 v57, v48
	v_pk_add_f32 v[54:55], v[122:123], v[54:55]
	v_mov_b32_e32 v58, v48
	v_pk_add_f32 v[54:55], v[124:125], v[54:55]
	v_mfma_f32_32x32x16_bf16 v[32:47], v[110:113], v[50:53], v[32:47]
	v_add_f32_e64 v54, v126, v54
	v_add_f32_e64 v55, v127, v55
	v_cvt_pk_bf16_f32 v52, v100, v101
	v_add_f32_e64 v50, v144, v54
	v_add_f32_e64 v51, v145, v55
	v_cvt_pk_bf16_f32 v53, v104, v105
	v_pk_add_f32 v[50:51], v[98:99], v[50:51]
	v_mov_b32_e32 v59, v48
	v_pk_add_f32 v[54:55], v[146:147], v[50:51]
	v_cvt_pk_bf16_f32 v50, v126, v127
	v_cvt_pk_bf16_f32 v51, v98, v99
	v_pk_add_f32 v[54:55], v[100:101], v[54:55]
	v_mov_b32_e32 v60, v48
	v_mfma_f32_32x32x16_bf16 v[64:79], v[90:93], v[50:53], v[64:79]
	v_add_f32_e64 v54, v102, v54
	v_add_f32_e64 v55, v103, v55
	v_mov_b32_e32 v61, v48
	v_add_f32_e64 v54, v104, v54
	v_add_f32_e64 v55, v105, v55
	v_mov_b32_e32 v62, v48
	v_pk_add_f32 v[54:55], v[54:55], v[54:55] op_sel_hi:[0,1]
	v_mov_b32_e32 v81, v55
	v_pk_add_f32 v[200:201], v[80:81], 0 op_sel_hi:[1,0]
	v_mfma_f32_32x32x16_bf16 v[32:47], v[106:109], v[50:53], v[32:47]
	v_add_f32_e64 v80, -v200, neg(0)
	v_add_f32_e64 v81, -v201, neg(0)
	v_mov_b32_e32 v50, v48
	v_mov_b32_e32 v81, v80
	v_mov_b32_e32 v82, v80
	v_mov_b32_e32 v83, v80
	v_mov_b32_e32 v84, v80
	v_mov_b32_e32 v85, v80
	v_mov_b32_e32 v86, v80
	v_mov_b32_e32 v87, v80
	v_mov_b32_e32 v88, v80
	v_mov_b32_e32 v89, v80
	v_mov_b32_e32 v90, v80
	v_mov_b32_e32 v91, v80
	v_mov_b32_e32 v92, v80
	v_mov_b32_e32 v93, v80
	v_mov_b32_e32 v94, v80
	v_mov_b32_e32 v95, v80
	v_mov_b32_e32 v51, v48
	v_mov_b32_e32 v52, v48
	v_mov_b32_e32 v53, v48
	v_mov_b32_e32 v54, v48
	v_mov_b32_e32 v55, v48
	v_mov_b32_e32 v63, v48
	v_readlane_b32 s99, v255, 23
.LBB0_735:
	s_cmp_eq_u32 s99, 0
	s_cbranch_scc1 .Lm3b_loop
	s_add_i32 s8, s6, -1
	s_min_i32 s9, s6, 35
	s_cmp_lt_u32 s8, 31
	s_cselect_b32 s15, 0, 0xffffffe0
	s_cselect_b32 s16, s13, s14
	s_add_i32 s15, s15, s9
	s_lshl_b32 s9, s15, 6
	s_add_i32 s9, s9, s16
	s_and_b32 s16, s8, 1
	s_mul_i32 s15, s16, 0x3400
	s_mulk_i32 s16, 0x3000
	v_add_u32_e32 v244, s15, v184
	v_add_u32_e32 v246, s16, v243
	ds_read_b128 v[218:221], v244
	ds_read_b128 v[222:225], v244 offset:6656
	ds_read_b128 v[226:229], v244 offset:32
	ds_read_b128 v[230:233], v244 offset:6688
	ds_read_b128 v[168:171], v244 offset:64
	ds_read_b128 v[172:175], v244 offset:6720
	ds_read_b128 v[176:179], v244 offset:96
	ds_read_b128 v[180:183], v244 offset:6752
	s_waitcnt lgkmcnt(7)
	v_mfma_f32_32x32x16_bf16 v[96:111], v[218:221], v[128:131], v[48:63]
	s_waitcnt lgkmcnt(6)
	v_mfma_f32_32x32x16_bf16 v[112:127], v[222:225], v[128:131], v[48:63]
	s_waitcnt lgkmcnt(5)
	v_mfma_f32_32x32x16_bf16 v[96:111], v[226:229], v[132:135], v[96:111]
	s_waitcnt lgkmcnt(4)
	v_mfma_f32_32x32x16_bf16 v[112:127], v[230:233], v[132:135], v[112:127]
	ds_read_b64_tr_b16 v[152:153], v246 offset:26624
	ds_read_b64_tr_b16 v[154:155], v246 offset:28160
	ds_read_b64_tr_b16 v[156:157], v246 offset:26688
	ds_read_b64_tr_b16 v[158:159], v246 offset:28224
	ds_read_b64_tr_b16 v[160:161], v246 offset:29696
	ds_read_b64_tr_b16 v[162:163], v246 offset:31232
	ds_read_b64_tr_b16 v[164:165], v246 offset:29760
	ds_read_b64_tr_b16 v[166:167], v246 offset:31296
	v_add_u32_e32 v186, s9, v239
	v_mad_i64_i32 v[186:187], s[16:17], v186, s33, v[194:195]
	v_add_u32_e32 v188, s9, v240
	v_mad_i64_i32 v[188:189], s[16:17], v188, s33, v[196:197]
	global_load_dwordx4 v[148:151], v[186:187], off
	global_load_dwordx4 v[144:147], v[188:189], off
	s_waitcnt lgkmcnt(11)
	v_mfma_f32_32x32x16_bf16 v[202:217], v[168:171], v[136:139], v[80:95]
	v_exp_f32_e32 v96, v96
	v_exp_f32_e32 v97, v97
	v_exp_f32_e32 v98, v98
	s_waitcnt lgkmcnt(10)
	v_mfma_f32_32x32x16_bf16 v[218:233], v[172:175], v[136:139], v[80:95]
	v_exp_f32_e32 v99, v99
	v_exp_f32_e32 v100, v100
	v_exp_f32_e32 v101, v101
	s_waitcnt lgkmcnt(9)
	v_mfma_f32_32x32x16_bf16 v[202:217], v[176:179], v[140:143], v[202:217]
	v_exp_f32_e32 v102, v102
	v_exp_f32_e32 v103, v103
	v_add_f32_e32 v234, v96, v98
	v_add_f32_e32 v235, v97, v99
	s_waitcnt lgkmcnt(8)
	v_mfma_f32_32x32x16_bf16 v[218:233], v[180:183], v[140:143], v[218:233]
	v_add_f32_e32 v234, v234, v100
	v_add_f32_e32 v235, v235, v101
	v_add_f32_e32 v234, v234, v102
	v_add_f32_e32 v235, v235, v103
	v_cvt_pk_bf16_f32 v96, v96, v97
	v_cvt_pk_bf16_f32 v97, v98, v99
	s_waitcnt lgkmcnt(7)
	ds_read_b64_tr_b16 v[168:169], v246 offset:32768
	ds_read_b64_tr_b16 v[170:171], v246 offset:34304
	ds_read_b64_tr_b16 v[172:173], v246 offset:32832
	ds_read_b64_tr_b16 v[174:175], v246 offset:34368
	ds_read_b64_tr_b16 v[176:177], v246 offset:35840
	ds_read_b64_tr_b16 v[178:179], v246 offset:37376
	ds_read_b64_tr_b16 v[180:181], v246 offset:35904
	ds_read_b64_tr_b16 v[182:183], v246 offset:37440
	v_cvt_pk_bf16_f32 v98, v100, v101
	v_cvt_pk_bf16_f32 v99, v102, v103
	v_exp_f32_e32 v104, v104
	v_exp_f32_e32 v105, v105
	s_waitcnt lgkmcnt(14)
	v_mfma_f32_32x32x16_bf16 v[16:31], v[152:155], v[96:99], v[16:31]
	v_exp_f32_e32 v106, v106
	v_exp_f32_e32 v107, v107
	v_exp_f32_e32 v108, v108
	s_waitcnt lgkmcnt(12)
	v_mfma_f32_32x32x16_bf16 v[0:15], v[156:159], v[96:99], v[0:15]
	v_exp_f32_e32 v109, v109
	v_exp_f32_e32 v110, v110
	v_exp_f32_e32 v111, v111
	v_add_f32_e32 v234, v234, v104
	v_add_f32_e32 v235, v235, v105
	v_add_f32_e32 v234, v234, v106
	v_add_f32_e32 v235, v235, v107
	v_add_f32_e32 v234, v234, v108
	v_add_f32_e32 v235, v235, v109
	v_add_f32_e32 v234, v234, v110
	v_add_f32_e32 v235, v235, v111
	v_cvt_pk_bf16_f32 v104, v104, v105
	v_cvt_pk_bf16_f32 v105, v106, v107
	v_cvt_pk_bf16_f32 v106, v108, v109
	v_cvt_pk_bf16_f32 v107, v110, v111
	v_exp_f32_e32 v112, v112
	v_exp_f32_e32 v113, v113
	s_waitcnt lgkmcnt(10)
	v_mfma_f32_32x32x16_bf16 v[16:31], v[160:163], v[104:107], v[16:31]
	v_exp_f32_e32 v114, v114
	v_exp_f32_e32 v115, v115
	v_exp_f32_e32 v116, v116
	s_waitcnt lgkmcnt(8)
	v_mfma_f32_32x32x16_bf16 v[0:15], v[164:167], v[104:107], v[0:15]
	v_exp_f32_e32 v117, v117
	v_exp_f32_e32 v118, v118
	v_exp_f32_e32 v119, v119
	v_add_f32_e32 v234, v234, v112
	v_add_f32_e32 v235, v235, v113
	v_add_f32_e32 v234, v234, v114
	v_add_f32_e32 v235, v235, v115
	v_add_f32_e32 v234, v234, v116
	v_add_f32_e32 v235, v235, v117
	v_add_f32_e32 v234, v234, v118
	v_add_f32_e32 v235, v235, v119
	v_cvt_pk_bf16_f32 v112, v112, v113
	v_cvt_pk_bf16_f32 v113, v114, v115
	v_cvt_pk_bf16_f32 v114, v116, v117
	v_cvt_pk_bf16_f32 v115, v118, v119
	v_exp_f32_e32 v120, v120
	v_exp_f32_e32 v121, v121
	s_waitcnt lgkmcnt(6)
	v_mfma_f32_32x32x16_bf16 v[16:31], v[168:171], v[112:115], v[16:31]
	v_exp_f32_e32 v122, v122
	v_exp_f32_e32 v123, v123
	v_exp_f32_e32 v124, v124
	s_waitcnt lgkmcnt(4)
	v_mfma_f32_32x32x16_bf16 v[0:15], v[172:175], v[112:115], v[0:15]
	v_exp_f32_e32 v125, v125
	v_exp_f32_e32 v126, v126
	v_exp_f32_e32 v127, v127
	v_add_f32_e32 v234, v234, v120
	v_add_f32_e32 v235, v235, v121
	v_add_f32_e32 v234, v234, v122
	v_add_f32_e32 v235, v235, v123
	v_add_f32_e32 v234, v234, v124
	v_add_f32_e32 v235, v235, v125
	v_add_f32_e32 v234, v234, v126
	v_add_f32_e32 v235, v235, v127
	v_cvt_pk_bf16_f32 v120, v120, v121
	v_cvt_pk_bf16_f32 v121, v122, v123
	v_cvt_pk_bf16_f32 v122, v124, v125
	v_cvt_pk_bf16_f32 v123, v126, v127
	v_exp_f32_e32 v202, v202
	v_exp_f32_e32 v203, v203
	s_waitcnt lgkmcnt(2)
	v_mfma_f32_32x32x16_bf16 v[16:31], v[176:179], v[120:123], v[16:31]
	v_exp_f32_e32 v204, v204
	v_exp_f32_e32 v205, v205
	v_exp_f32_e32 v206, v206
	s_waitcnt lgkmcnt(0)
	v_mfma_f32_32x32x16_bf16 v[0:15], v[180:183], v[120:123], v[0:15]
	v_exp_f32_e32 v207, v207
	v_exp_f32_e32 v208, v208
	v_exp_f32_e32 v209, v209
	s_cmp_gt_u32 s8, 34
	s_cbranch_scc1 .Lm3a_skipw
	s_and_b32 s8, s7, 64
	s_mul_i32 s9, s8, 0xd0
	s_mulk_i32 s8, 0xc0
	v_add_u32_e32 v186, s9, v241
	v_add_u32_e32 v188, s8, v242
	s_waitcnt vmcnt(1)
	ds_write_b128 v186, v[148:151]
	s_waitcnt vmcnt(0)
	ds_write_b128 v188, v[144:147] offset:26624

.Lm3b_loop:
	s_add_i32 s8, s6, -1
	s_min_i32 s9, s6, 35
	s_cmp_lt_u32 s8, 31
	s_cselect_b32 s15, 0, 0xffffffe0
	s_cselect_b32 s16, s13, s14
	s_add_i32 s15, s15, s9
	s_lshl_b32 s9, s15, 6
	s_add_i32 s9, s9, s16
	s_and_b32 s16, s8, 1
	s_mul_i32 s15, s16, 0x3400
	s_mulk_i32 s16, 0x3000
	v_add_u32_e32 v244, s15, v184
	v_add_u32_e32 v246, s16, v243
	ds_read_b128 v[218:221], v244
	ds_read_b128 v[222:225], v244 offset:6656
	ds_read_b128 v[226:229], v244 offset:32
	ds_read_b128 v[230:233], v244 offset:6688
	ds_read_b128 v[168:171], v244 offset:64
	ds_read_b128 v[172:175], v244 offset:6720
	ds_read_b128 v[176:179], v244 offset:96
	ds_read_b128 v[180:183], v244 offset:6752
	s_cmp_lg_u32 s99, 0
	s_cbranch_scc1 .Lm3b_pf
	s_cmp_eq_u32 s6, 2
	s_cbranch_scc0 .Lm3b_nopf
.Lm3b_pf:
	v_add_u32_e32 v186, s9, v239
	v_mad_i64_i32 v[186:187], s[16:17], v186, s33, v[194:195]
	v_add_u32_e32 v188, s9, v240
	v_mad_i64_i32 v[188:189], s[16:17], v188, s33, v[196:197]
	global_load_dwordx4 v[148:151], v[186:187], off
	global_load_dwordx4 v[144:147], v[188:189], off
.Lm3b_nopf:
	s_waitcnt lgkmcnt(7)
	v_mfma_f32_32x32x16_bf16 v[96:111], v[218:221], v[128:131], v[48:63]
	s_waitcnt lgkmcnt(6)
	v_mfma_f32_32x32x16_bf16 v[112:127], v[222:225], v[128:131], v[48:63]
	s_waitcnt lgkmcnt(5)
	v_mfma_f32_32x32x16_bf16 v[96:111], v[226:229], v[132:135], v[96:111]
	s_waitcnt lgkmcnt(4)
	v_mfma_f32_32x32x16_bf16 v[112:127], v[230:233], v[132:135], v[112:127]
	s_waitcnt lgkmcnt(3)
	v_mfma_f32_32x32x16_bf16 v[202:217], v[168:171], v[136:139], v[80:95]
	s_waitcnt lgkmcnt(2)
	v_mfma_f32_32x32x16_bf16 v[218:233], v[172:175], v[136:139], v[80:95]
	s_waitcnt lgkmcnt(1)
	v_mfma_f32_32x32x16_bf16 v[202:217], v[176:179], v[140:143], v[202:217]
	s_waitcnt lgkmcnt(0)
	v_mfma_f32_32x32x16_bf16 v[218:233], v[180:183], v[140:143], v[218:233]
	ds_read_b64_tr_b16 v[152:153], v246 offset:26624
	ds_read_b64_tr_b16 v[154:155], v246 offset:28160
	ds_read_b64_tr_b16 v[156:157], v246 offset:26688
	ds_read_b64_tr_b16 v[158:159], v246 offset:28224
	ds_read_b64_tr_b16 v[160:161], v246 offset:29696
	ds_read_b64_tr_b16 v[162:163], v246 offset:31232
	ds_read_b64_tr_b16 v[164:165], v246 offset:29760
	ds_read_b64_tr_b16 v[166:167], v246 offset:31296
	ds_read_b64_tr_b16 v[168:169], v246 offset:32768
	ds_read_b64_tr_b16 v[170:171], v246 offset:34304
	ds_read_b64_tr_b16 v[172:173], v246 offset:32832
	ds_read_b64_tr_b16 v[174:175], v246 offset:34368
	ds_read_b64_tr_b16 v[176:177], v246 offset:35840
	ds_read_b64_tr_b16 v[178:179], v246 offset:37376
	ds_read_b64_tr_b16 v[180:181], v246 offset:35904
	ds_read_b64_tr_b16 v[182:183], v246 offset:37440
	s_cmp_eq_u32 s99, 0
	s_cbranch_scc0 .Lm3b_x
	s_cmp_gt_u32 s8, 34
	s_cbranch_scc1 .Lm3b_skipwx
	s_and_b32 s8, s7, 64
	s_mul_i32 s9, s8, 0xd0
	s_mulk_i32 s8, 0xc0
	v_add_u32_e32 v186, s9, v241
	v_add_u32_e32 v188, s8, v242
	s_waitcnt vmcnt(1)
	ds_write_b128 v186, v[148:151]
	s_waitcnt vmcnt(0)
	ds_write_b128 v188, v[144:147] offset:26624
.Lm3b_skipwx:
	s_waitcnt lgkmcnt(0)
	s_barrier
	s_add_i32 s9, s6, 1
	s_min_i32 s9, s9, 35
	s_cmp_lt_u32 s6, 31
	s_cselect_b32 s15, 0, 0xffffffe0
	s_cselect_b32 s16, s13, s14
	s_add_i32 s15, s15, s9
	s_lshl_b32 s9, s15, 6
	s_add_i32 s9, s9, s16
	v_add_u32_e32 v186, s9, v239
	v_mad_i64_i32 v[186:187], s[16:17], v186, s33, v[194:195]
	v_add_u32_e32 v188, s9, v240
	v_mad_i64_i32 v[188:189], s[16:17], v188, s33, v[196:197]
	global_load_dwordx4 v[148:151], v[186:187], off
	global_load_dwordx4 v[144:147], v[188:189], off
.Lm3b_x:
	v_exp_f32_e32 v96, v96
	v_exp_f32_e32 v97, v97
	v_exp_f32_e32 v98, v98
	v_exp_f32_e32 v99, v99
	v_exp_f32_e32 v100, v100
	v_exp_f32_e32 v101, v101
	v_exp_f32_e32 v102, v102
	v_exp_f32_e32 v103, v103
	v_add_f32_e32 v234, v96, v98
	v_add_f32_e32 v235, v97, v99
	v_add_f32_e32 v234, v234, v100
	v_add_f32_e32 v235, v235, v101
	v_add_f32_e32 v234, v234, v102
	v_add_f32_e32 v235, v235, v103
	v_cvt_pk_bf16_f32 v96, v96, v97
	v_cvt_pk_bf16_f32 v97, v98, v99
	v_cvt_pk_bf16_f32 v98, v100, v101
	v_cvt_pk_bf16_f32 v99, v102, v103
	v_exp_f32_e32 v104, v104
	v_exp_f32_e32 v105, v105
	s_waitcnt lgkmcnt(14)
	v_mfma_f32_32x32x16_bf16 v[16:31], v[152:155], v[96:99], v[16:31]
	v_exp_f32_e32 v106, v106
	v_exp_f32_e32 v107, v107
	v_exp_f32_e32 v108, v108
	s_waitcnt lgkmcnt(12)
	v_mfma_f32_32x32x16_bf16 v[0:15], v[156:159], v[96:99], v[0:15]
	v_exp_f32_e32 v109, v109
	v_exp_f32_e32 v110, v110
	v_exp_f32_e32 v111, v111
	v_add_f32_e32 v234, v234, v104
	v_add_f32_e32 v235, v235, v105
	v_add_f32_e32 v234, v234, v106
	v_add_f32_e32 v235, v235, v107
	v_add_f32_e32 v234, v234, v108
	v_add_f32_e32 v235, v235, v109
	v_add_f32_e32 v234, v234, v110
	v_add_f32_e32 v235, v235, v111
	v_cvt_pk_bf16_f32 v104, v104, v105
	v_cvt_pk_bf16_f32 v105, v106, v107
	v_cvt_pk_bf16_f32 v106, v108, v109
	v_cvt_pk_bf16_f32 v107, v110, v111
	v_exp_f32_e32 v112, v112
	v_exp_f32_e32 v113, v113
	s_waitcnt lgkmcnt(10)
	v_mfma_f32_32x32x16_bf16 v[16:31], v[160:163], v[104:107], v[16:31]
	v_exp_f32_e32 v114, v114
	v_exp_f32_e32 v115, v115
	v_exp_f32_e32 v116, v116
	s_waitcnt lgkmcnt(8)
	v_mfma_f32_32x32x16_bf16 v[0:15], v[164:167], v[104:107], v[0:15]
	v_exp_f32_e32 v117, v117
	v_exp_f32_e32 v118, v118
	v_exp_f32_e32 v119, v119
	v_add_f32_e32 v234, v234, v112
	v_add_f32_e32 v235, v235, v113
	v_add_f32_e32 v234, v234, v114
	v_add_f32_e32 v235, v235, v115
	v_add_f32_e32 v234, v234, v116
	v_add_f32_e32 v235, v235, v117
	v_add_f32_e32 v234, v234, v118
	v_add_f32_e32 v235, v235, v119
	v_cvt_pk_bf16_f32 v112, v112, v113
	v_cvt_pk_bf16_f32 v113, v114, v115
	v_cvt_pk_bf16_f32 v114, v116, v117
	v_cvt_pk_bf16_f32 v115, v118, v119
	v_exp_f32_e32 v120, v120
	v_exp_f32_e32 v121, v121
	s_waitcnt lgkmcnt(6)
	v_mfma_f32_32x32x16_bf16 v[16:31], v[168:171], v[112:115], v[16:31]
	v_exp_f32_e32 v122, v122
	v_exp_f32_e32 v123, v123
	v_exp_f32_e32 v124, v124
	s_waitcnt lgkmcnt(4)
	v_mfma_f32_32x32x16_bf16 v[0:15], v[172:175], v[112:115], v[0:15]
	v_exp_f32_e32 v125, v125
	v_exp_f32_e32 v126, v126
	v_exp_f32_e32 v127, v127
	v_add_f32_e32 v234, v234, v120
	v_add_f32_e32 v235, v235, v121
	v_add_f32_e32 v234, v234, v122
	v_add_f32_e32 v235, v235, v123
	v_add_f32_e32 v234, v234, v124
	v_add_f32_e32 v235, v235, v125
	v_add_f32_e32 v234, v234, v126
	v_add_f32_e32 v235, v235, v127
	v_cvt_pk_bf16_f32 v120, v120, v121
	v_cvt_pk_bf16_f32 v121, v122, v123
	v_cvt_pk_bf16_f32 v122, v124, v125
	v_cvt_pk_bf16_f32 v123, v126, v127
	v_exp_f32_e32 v202, v202
	v_exp_f32_e32 v203, v203
	s_waitcnt lgkmcnt(2)
	v_mfma_f32_32x32x16_bf16 v[16:31], v[176:179], v[120:123], v[16:31]
	v_exp_f32_e32 v204, v204
	v_exp_f32_e32 v205, v205
	v_exp_f32_e32 v206, v206
	s_waitcnt lgkmcnt(0)
	v_mfma_f32_32x32x16_bf16 v[0:15], v[180:183], v[120:123], v[0:15]
	v_exp_f32_e32 v207, v207
	v_exp_f32_e32 v208, v208
	v_exp_f32_e32 v209, v209
	s_cmp_eq_u32 s99, 0
	s_cbranch_scc1 .Lm3b_skipwy
	s_cmp_gt_u32 s8, 34
	s_cbranch_scc1 .Lm3b_skipwy
	s_and_b32 s8, s7, 64
	s_mul_i32 s9, s8, 0xd0
	s_mulk_i32 s8, 0xc0
	v_add_u32_e32 v186, s9, v241
	v_add_u32_e32 v188, s8, v242
	s_waitcnt vmcnt(1)
	ds_write_b128 v186, v[148:151]
	s_waitcnt vmcnt(0)
	ds_write_b128 v188, v[144:147] offset:26624
.Lm3b_skipwy:
	v_add_f32_e32 v236, v202, v204
	v_add_f32_e32 v237, v203, v205
	v_add_f32_e32 v236, v236, v206
	v_add_f32_e32 v237, v237, v207
	v_add_f32_e32 v236, v236, v208
	v_add_f32_e32 v237, v237, v209
	v_cvt_pk_bf16_f32 v202, v202, v203
	v_cvt_pk_bf16_f32 v203, v204, v205
	v_cvt_pk_bf16_f32 v204, v206, v207
	v_cvt_pk_bf16_f32 v205, v208, v209
	v_exp_f32_e32 v210, v210
	v_exp_f32_e32 v211, v211
	v_mfma_f32_32x32x16_bf16 v[64:79], v[152:155], v[202:205], v[64:79]
	v_exp_f32_e32 v212, v212
	v_exp_f32_e32 v213, v213
	v_exp_f32_e32 v214, v214
	v_mfma_f32_32x32x16_bf16 v[32:47], v[156:159], v[202:205], v[32:47]
	v_exp_f32_e32 v215, v215
	v_exp_f32_e32 v216, v216
	v_exp_f32_e32 v217, v217
	v_add_f32_e32 v236, v236, v210
	v_add_f32_e32 v237, v237, v211
	v_add_f32_e32 v236, v236, v212
	v_add_f32_e32 v237, v237, v213
	v_add_f32_e32 v236, v236, v214
	v_add_f32_e32 v237, v237, v215
	v_add_f32_e32 v236, v236, v216
	v_add_f32_e32 v237, v237, v217
	v_cvt_pk_bf16_f32 v210, v210, v211
	v_cvt_pk_bf16_f32 v211, v212, v213
	v_cvt_pk_bf16_f32 v212, v214, v215
	v_cvt_pk_bf16_f32 v213, v216, v217
	v_exp_f32_e32 v218, v218
	v_exp_f32_e32 v219, v219
	v_mfma_f32_32x32x16_bf16 v[64:79], v[160:163], v[210:213], v[64:79]
	v_exp_f32_e32 v220, v220
	v_exp_f32_e32 v221, v221
	v_exp_f32_e32 v222, v222
	v_mfma_f32_32x32x16_bf16 v[32:47], v[164:167], v[210:213], v[32:47]
	v_exp_f32_e32 v223, v223
	v_exp_f32_e32 v224, v224
	v_exp_f32_e32 v225, v225
	v_add_f32_e32 v236, v236, v218
	v_add_f32_e32 v237, v237, v219
	v_add_f32_e32 v236, v236, v220
	v_add_f32_e32 v237, v237, v221
	v_add_f32_e32 v236, v236, v222
	v_add_f32_e32 v237, v237, v223
	v_add_f32_e32 v236, v236, v224
	v_add_f32_e32 v237, v237, v225
	v_cvt_pk_bf16_f32 v218, v218, v219
	v_cvt_pk_bf16_f32 v219, v220, v221
	v_cvt_pk_bf16_f32 v220, v222, v223
	v_cvt_pk_bf16_f32 v221, v224, v225
	v_exp_f32_e32 v226, v226
	v_exp_f32_e32 v227, v227
	v_mfma_f32_32x32x16_bf16 v[64:79], v[168:171], v[218:221], v[64:79]
	v_exp_f32_e32 v228, v228
	v_exp_f32_e32 v229, v229
	v_exp_f32_e32 v230, v230
	v_mfma_f32_32x32x16_bf16 v[32:47], v[172:175], v[218:221], v[32:47]
	v_exp_f32_e32 v231, v231
	v_exp_f32_e32 v232, v232
	v_exp_f32_e32 v233, v233
	v_add_f32_e32 v236, v236, v226
	v_add_f32_e32 v237, v237, v227
	v_add_f32_e32 v236, v236, v228
	v_add_f32_e32 v237, v237, v229
	v_add_f32_e32 v236, v236, v230
	v_add_f32_e32 v237, v237, v231
	v_add_f32_e32 v236, v236, v232
	v_add_f32_e32 v237, v237, v233
	v_cvt_pk_bf16_f32 v226, v226, v227
	v_cvt_pk_bf16_f32 v227, v228, v229
	v_cvt_pk_bf16_f32 v228, v230, v231
	v_cvt_pk_bf16_f32 v229, v232, v233
	s_nop 1
	v_mfma_f32_32x32x16_bf16 v[64:79], v[176:179], v[226:229], v[64:79]
	v_mfma_f32_32x32x16_bf16 v[32:47], v[180:183], v[226:229], v[32:47]
	v_add_f32_e32 v234, v234, v235
	v_add_f32_e32 v236, v236, v237
	v_add_f32_e32 v199, v199, v234
	v_add_f32_e32 v201, v201, v236
	v_max_f32_e32 v247, v234, v236
	v_cmp_lt_f32_e32 vcc, 0x43000000, v247
	s_cbranch_vccz .Lm3b_norescale
	s_nop 15
	v_mov_b32_e32 v235, v234
	s_nop 1
	v_permlane32_swap_b32_e32 v234, v235
	v_add_f32_e32 v247, v234, v235
	v_cmp_lt_f32_e32 vcc, 0x43800000, v247
	v_frexp_exp_i32_f32_e32 v248, v247
	s_nop 1
	v_cndmask_b32_e32 v248, 0, v248, vcc
	v_cvt_f32_i32_e32 v249, v248
	v_sub_u32_e32 v248, 0, v248
	v_ldexp_f32 v247, 1.0, v248
	v_add_f32_e32 v198, v198, v249
	v_mul_f32_e32 v199, v199, v247
	v_mul_f32_e32 v16, v16, v247
	v_mul_f32_e32 v17, v17, v247
	v_mul_f32_e32 v18, v18, v247
	v_mul_f32_e32 v19, v19, v247
	v_mul_f32_e32 v20, v20, v247
	v_mul_f32_e32 v21, v21, v247
	v_mul_f32_e32 v22, v22, v247
	v_mul_f32_e32 v23, v23, v247
	v_mul_f32_e32 v24, v24, v247
	v_mul_f32_e32 v25, v25, v247
	v_mul_f32_e32 v26, v26, v247
	v_mul_f32_e32 v27, v27, v247
	v_mul_f32_e32 v28, v28, v247
	v_mul_f32_e32 v29, v29, v247
	v_mul_f32_e32 v30, v30, v247
	v_mul_f32_e32 v31, v31, v247
	v_mul_f32_e32 v0, v0, v247
	v_mul_f32_e32 v1, v1, v247
	v_mul_f32_e32 v2, v2, v247
	v_mul_f32_e32 v3, v3, v247
	v_mul_f32_e32 v4, v4, v247
	v_mul_f32_e32 v5, v5, v247
	v_mul_f32_e32 v6, v6, v247
	v_mul_f32_e32 v7, v7, v247
	v_mul_f32_e32 v8, v8, v247
	v_mul_f32_e32 v9, v9, v247
	v_mul_f32_e32 v10, v10, v247
	v_mul_f32_e32 v11, v11, v247
	v_mul_f32_e32 v12, v12, v247
	v_mul_f32_e32 v13, v13, v247
	v_mul_f32_e32 v14, v14, v247
	v_mul_f32_e32 v15, v15, v247
	v_sub_f32_e32 v48, 0, v198
	v_mov_b32_e32 v49, v48
	v_mov_b32_e32 v50, v48
	v_mov_b32_e32 v51, v48
	v_mov_b32_e32 v52, v48
	v_mov_b32_e32 v53, v48
	v_mov_b32_e32 v54, v48
	v_mov_b32_e32 v55, v48
	v_mov_b32_e32 v56, v48
	v_mov_b32_e32 v57, v48
	v_mov_b32_e32 v58, v48
	v_mov_b32_e32 v59, v48
	v_mov_b32_e32 v60, v48
	v_mov_b32_e32 v61, v48
	v_mov_b32_e32 v62, v48
	v_mov_b32_e32 v63, v48
	v_mov_b32_e32 v237, v236
	s_nop 1
	v_permlane32_swap_b32_e32 v236, v237
	v_add_f32_e32 v247, v236, v237
	v_cmp_lt_f32_e32 vcc, 0x43800000, v247
	v_frexp_exp_i32_f32_e32 v248, v247
	s_nop 1
	v_cndmask_b32_e32 v248, 0, v248, vcc
	v_cvt_f32_i32_e32 v249, v248
	v_sub_u32_e32 v248, 0, v248
	v_ldexp_f32 v247, 1.0, v248
	v_add_f32_e32 v200, v200, v249
	v_mul_f32_e32 v201, v201, v247
	v_mul_f32_e32 v64, v64, v247
	v_mul_f32_e32 v65, v65, v247
	v_mul_f32_e32 v66, v66, v247
	v_mul_f32_e32 v67, v67, v247
	v_mul_f32_e32 v68, v68, v247
	v_mul_f32_e32 v69, v69, v247
	v_mul_f32_e32 v70, v70, v247
	v_mul_f32_e32 v71, v71, v247
	v_mul_f32_e32 v72, v72, v247
	v_mul_f32_e32 v73, v73, v247
	v_mul_f32_e32 v74, v74, v247
	v_mul_f32_e32 v75, v75, v247
	v_mul_f32_e32 v76, v76, v247
	v_mul_f32_e32 v77, v77, v247
	v_mul_f32_e32 v78, v78, v247
	v_mul_f32_e32 v79, v79, v247
	v_mul_f32_e32 v32, v32, v247
	v_mul_f32_e32 v33, v33, v247
	v_mul_f32_e32 v34, v34, v247
	v_mul_f32_e32 v35, v35, v247
	v_mul_f32_e32 v36, v36, v247
	v_mul_f32_e32 v37, v37, v247
	v_mul_f32_e32 v38, v38, v247
	v_mul_f32_e32 v39, v39, v247
	v_mul_f32_e32 v40, v40, v247
	v_mul_f32_e32 v41, v41, v247
	v_mul_f32_e32 v42, v42, v247
	v_mul_f32_e32 v43, v43, v247
	v_mul_f32_e32 v44, v44, v247
	v_mul_f32_e32 v45, v45, v247
	v_mul_f32_e32 v46, v46, v247
	v_mul_f32_e32 v47, v47, v247
	v_sub_f32_e32 v80, 0, v200
	v_mov_b32_e32 v81, v80
	v_mov_b32_e32 v82, v80
	v_mov_b32_e32 v83, v80
	v_mov_b32_e32 v84, v80
	v_mov_b32_e32 v85, v80
	v_mov_b32_e32 v86, v80
	v_mov_b32_e32 v87, v80
	v_mov_b32_e32 v88, v80
	v_mov_b32_e32 v89, v80
	v_mov_b32_e32 v90, v80
	v_mov_b32_e32 v91, v80
	v_mov_b32_e32 v92, v80
	v_mov_b32_e32 v93, v80
	v_mov_b32_e32 v94, v80
	v_mov_b32_e32 v95, v80
.Lm3b_norescale:
	s_cmp_eq_u32 s99, 0
	s_cbranch_scc1 .Lm3b_z
	s_waitcnt lgkmcnt(0)
	s_barrier
.Lm3b_z:
	s_add_i32 s7, s7, 64
	s_add_i32 s6, s6, 1
	s_cmpk_lg_i32 s7, 0x940
	s_cbranch_scc1 .LBB0_735
	v_mov_b32_e32 v98, v199
	v_mov_b32_e32 v96, v201
	s_branch .LBB0_733
